# S37: S36 + ctx-unit attention prologue: compiler vmcnt(0) before the first QK MFMA relaxed to lgkmcnt(0) (wait placement at first consumer; Q covered by the earlier counted vmcnt(4))
# speedup vs baseline: 1.0047x; 1.0008x over previous
; __device__ __forceinline__ int v_rd_base(int lane) { return ((lane & 3) << 3) | (((lane >> 2) & 3) << 6) | (((lane >> 4) & 1) << 5) | (((lane >> 5) & 1) << 8); }
; __device__ __forceinline__ void attn_unit(const bf16* __restrict__ Qb, const bf16* __restrict__ Kh, const bf16* __restrict__ Vh, int klat0, int nlt, int kctx0, int NT,
;                                           float lam, float post, const float* __restrict__ subw, bf16* __restrict__ Ob, char* lds) {
;     ...
;   const int tid = tid_l, wid = __builtin_amdgcn_readfirstlane(tid >> 6), lane = tid & 63, r32 = lane & 31, hi = lane >> 5;
;   const int sbr = wid >> 2, wq = wid & 3, sb = sbr * 128;
;   char* K_lds = lds + LDS_KR; char* V_lds = lds + LDS_VR;
;   float* ws = (float*)(lds + LDS_WS) + wid * 64; float* li_l = ws; float* al_l = ws + 32;
;   float m_reg = -1e30f, l_reg = 0; f32x16 o[4] = {}; bf16x8 qr[4];
;   const bf16* Qw = Qb + (long)(wq * 32 + r32) * LDK + sbr * 64 + hi * 8;
; #pragma unroll
;   for (int d0 = 0; d0 < 4; ++d0) qr[d0] = *reinterpret_cast<const bf16x8*>(Qw + d0 * 16);
;   unsigned koff[2], voff[2];
; #pragma unroll
;   for (int q = 0; q < 2; ++q) { const int ch = (q * 8 + wid) * 64 + lane;
;     { const int row = ch >> 4, cpos = ch & 15, csrc = cpos ^ (row & 7); koff[q] = (unsigned)(row * LDK + csrc * 8) * 2u; }
;     { const int pb = ch * 16, sub = pb >> 9, within = (pb & 511) >> 1, kk = (sub >> 2) * 8 + (within >> 5), c = (sub & 3) * 32 + (within & 31);
;       const int k = (kk & ~0xC) | ((kk & 4) << 1) | ((kk & 8) >> 1); voff[q] = (unsigned)(k * LDK + c) * 2u; } }
;   const int vb0 = (int)(uintptr_t)V_lds + v_rd_base(lane);
;   const unsigned ldsw = (unsigned)wid * 1024u;
;   typedef __attribute__((address_space(3))) unsigned lds_u32;
;     ...
;   f32x16 pA0, pA1, pB0, pB1; float mnA, mnB, alA, alB; bf16x8 pa0, pa1, pa2, pa3;
;   DMA_TILE(0); DMA_TILE(1); TILE_BAR(4);
;   DMA_TILE(2);
;   qkt(pA0, pA1, KS(0), qr, r32, hi, sb); partialSM(pA0, pA1, m_reg, mnA, alA);
; __global__ void __launch_bounds__(NWAVES * 64, 2) mk_fwd(Args args) {
;     ...
;                 else { const int uc = u - 1024, bh = uc >> 1, qb = uc & 1, b = bh >> 3, h = bh & 7; const size_t q0 = (size_t)NLAT + b * CTXL + qb * 128;
;                     att::attn_unit(Q + q0 * 1024 + h * 128, K + h * 128, V + h * 128, 0, 0, NLAT + b * CTXL, 4, lam, post, F.subln_w + l * 128, MIX + q0 * DM + h * 128, F.ldsg); } }
.LBB0_716:
	s_cmpk_gt_i32 s8, 0x3ff
	s_mov_b64 s[0:1], -1
	s_cbranch_scc0 .LBB0_748
	s_lshl_b32 s0, s8, 4
	s_lshl_b32 s1, s8, 7
	s_and_b32 s0, s0, 0x7fffff00
	s_and_b32 s1, s1, 0x80
	s_or_b32 s58, s0, s1
	s_lshl_b64 s[4:5], s[58:59], 11
	v_readlane_b32 s1, v249, 48
	s_add_u32 s1, s1, s4
	v_readlane_b32 s4, v249, 49
	s_addc_u32 s5, s4, s5
	s_lshl_b32 s4, s8, 6
	s_and_b32 s4, s4, 0x380
	s_lshl_b32 s9, s4, 1
	s_add_u32 s4, s1, s9
	s_addc_u32 s5, s5, 0
	v_readlane_b32 s1, v251, 17
	s_add_u32 s6, s1, s9
	v_readlane_b32 s1, v251, 18
	s_addc_u32 s7, s1, 0
	v_readlane_b32 s1, v251, 19
	v_mov_b32_e32 v4, v0
	s_add_u32 s17, s1, s9
	v_readlane_b32 s1, v251, 20
	s_addc_u32 s18, s1, 0
	v_readfirstlane_b32 s16, v4
	s_ashr_i32 s1, s16, 6
	v_and_b32_e32 v124, 31, v4
	s_and_b32 s12, s1, 3
	v_lshlrev_b32_e32 v2, 11, v124
	s_ashr_i32 s10, s16, 8
	v_lshl_or_b32 v146, s12, 16, v2
	v_lshl_add_u64 v[2:3], s[4:5], 0, v[146:147]
	s_lshl_b32 s4, s10, 6
	s_ashr_i32 s5, s4, 31
	v_bfe_u32 v5, v4, 2, 2
	v_lshrrev_b32_e32 v7, 1, v4
	v_bfe_u32 v125, v4, 5, 1
	s_and_b32 s13, s16, 0xffffffc0
	v_lshl_add_u64 v[2:3], s[4:5], 1, v[2:3]
	v_and_or_b32 v5, v7, 8, v5
	v_mov_b32_e32 v7, s16
	s_movk_i32 s4, 0xffc0
	v_lshlrev_b32_e32 v146, 4, v125
	v_bfi_b32 v7, s4, v7, v4
	s_ashr_i32 s4, s13, 4
	v_and_b32_e32 v66, 63, v4
	v_lshl_add_u64 v[2:3], v[2:3], 0, v[146:147]
	s_and_b32 s5, s4, 0x1ffff0
	s_lshr_b32 s4, s4, 1
	global_load_dwordx4 v[120:123], v[2:3], off
	global_load_dwordx4 v[116:119], v[2:3], off offset:32
	global_load_dwordx4 v[112:115], v[2:3], off offset:64
	global_load_dwordx4 v[108:111], v[2:3], off offset:96
	v_and_b32_e32 v2, 15, v4
	v_lshlrev_b32_e32 v3, 3, v66
	v_ashrrev_i32_e32 v8, 4, v7
	s_and_b32 s4, s4, 4
	s_lshl_b32 s11, s13, 2
	v_and_b32_e32 v6, 24, v3
	v_bitop3_b32 v9, v8, v2, 7 bitop3:0x6c
	v_lshlrev_b32_e32 v8, 11, v8
	s_movk_i32 s19, 0x60
	s_or_b32 s4, s5, s4
	s_addk_i32 s13, 0x200
	v_lshl_or_b32 v34, v9, 4, v8
	v_and_or_b32 v7, v7, s19, v6
	v_or_b32_e32 v8, s4, v5
	s_ashr_i32 s4, s13, 4
	v_lshlrev_b32_e32 v7, 1, v7
	s_and_b32 s5, s4, 0x1ffff0
	s_lshr_b32 s4, s4, 1
	s_add_i32 s11, s11, 0
	v_lshl_or_b32 v36, v8, 11, v7
	v_or_b32_e32 v7, s13, v66
	s_and_b32 s4, s4, 4
	s_lshl_b32 s13, s1, 10
	s_mov_b32 s1, s59
	s_add_i32 s11, s11, 0x1c000
	s_or_b32 s4, s5, s4
	s_lshl_b64 s[0:1], s[0:1], 11
	v_or_b32_e32 v5, s4, v5
	s_add_u32 s4, s6, s0
	s_addc_u32 s5, s7, s1
	s_add_u32 s20, s17, s0
	v_ashrrev_i32_e32 v8, 4, v7
	s_addc_u32 s21, s18, s1
	v_bitop3_b32 v2, v8, v2, 7 bitop3:0x6c
	v_lshlrev_b32_e32 v8, 11, v8
	s_cmp_lg_u32 0, -1
	v_lshl_or_b32 v38, v2, 4, v8
	v_and_or_b32 v2, v7, s19, v6
	s_cselect_b32 s19, 0, 0
	s_add_i32 s22, s13, s19
	s_add_i32 s19, s19, 0xc000
	s_add_i32 s23, s13, s19
	s_mov_b32 m0, s22
	v_lshlrev_b32_e32 v2, 1, v2
	global_load_lds_dwordx4 v34, s[4:5]
	s_mov_b32 m0, s23
	v_lshl_or_b32 v64, v5, 11, v2
	global_load_lds_dwordx4 v36, s[20:21]
	s_add_i32 m0, s22, 0x2000
	v_lshlrev_b32_e32 v2, 1, v4
	global_load_lds_dwordx4 v38, s[4:5]
	s_add_i32 m0, s22, 0xe000
	v_lshlrev_b32_e32 v4, 4, v4
	global_load_lds_dwordx4 v64, s[20:21]
	s_or_b32 s20, s0, 0x20000
	s_add_u32 s4, s6, s20
	s_addc_u32 s5, s7, s1
	s_add_u32 s20, s17, s20
	s_addc_u32 s21, s18, s1
	s_add_i32 m0, s22, 0x4000
	s_add_i32 s23, s22, 0x10000
	global_load_lds_dwordx4 v34, s[4:5]
	s_mov_b32 m0, s23
	v_lshl_or_b32 v10, s10, 7, v146
	global_load_lds_dwordx4 v36, s[20:21]
	s_add_i32 m0, s22, 0x6000
	v_and_b32_e32 v2, 32, v2
	global_load_lds_dwordx4 v38, s[4:5]
	s_add_i32 m0, s22, 0x12000
	v_lshlrev_b32_e32 v11, 8, v124
	global_load_lds_dwordx4 v64, s[20:21]
	s_or_b32 s20, s0, 0x40000
	s_add_u32 s4, s6, s20
	s_addc_u32 s5, s7, s1
	s_add_u32 s20, s17, s20
	s_waitcnt vmcnt(4)
	s_barrier
	s_addc_u32 s21, s18, s1
	s_add_i32 m0, s22, 0x8000
	s_add_i32 s23, s22, 0x14000
	global_load_lds_dwordx4 v34, s[4:5]
	s_mov_b32 m0, s23
	v_and_b32_e32 v12, 0x70, v4
	global_load_lds_dwordx4 v36, s[20:21]
	s_add_i32 m0, s22, 0xa000
	v_or_b32_e32 v13, 32, v10
	global_load_lds_dwordx4 v38, s[4:5]
	s_add_i32 m0, s22, 0x16000
	v_and_or_b32 v2, v4, s72, v2
	global_load_lds_dwordx4 v64, s[20:21]
	v_and_b32_e32 v3, 0x100, v3
	v_xad_u32 v13, v13, v12, v11
	v_or3_b32 v136, v2, v3, v6
	v_xad_u32 v2, v10, v12, v11
	v_add_u32_e32 v138, 0, v13
	v_or_b32_e32 v13, 64, v10
	v_or_b32_e32 v10, 0x60, v10
	v_xad_u32 v13, v13, v12, v11
	v_xad_u32 v10, v10, v12, v11
	v_add_u32_e32 v137, 0, v2
	v_add_u32_e32 v139, 0, v13
	v_add_u32_e32 v140, 0, v10
	ds_read_b128 v[2:5], v137
	ds_read_b128 v[6:9], v137 offset:8192
	ds_read_b128 v[40:43], v138
	ds_read_b128 v[44:47], v138 offset:8192
	ds_read_b128 v[48:51], v139
	ds_read_b128 v[52:55], v139 offset:8192
	ds_read_b128 v[56:59], v140
	ds_read_b128 v[60:63], v140 offset:8192
	v_mov_b32_e32 v35, v147
	v_mov_b32_e32 v37, v147
	v_mov_b32_e32 v39, v147
	v_mov_b32_e32 v65, v147
	v_add_u32_e32 v144, s19, v136
	s_waitcnt lgkmcnt(0)
	s_waitcnt lgkmcnt(0)
	v_mfma_f32_32x32x16_bf16 v[18:33], v[2:5], v[120:123], 0
	s_waitcnt vmcnt(4)
	s_barrier
; #define SBAR() __builtin_amdgcn_sched_barrier(0)
; __device__ __forceinline__ void partialSM(f32x16& p0, f32x16& p1, float& m_reg, float& mn, float& alpha) {
;   constexpr float C = SCALE * 1.4426950408889634f;
;   float pmax = p0[0]; for (int r = 1; r < 16; ++r) pmax = fmaxf(pmax, p0[r]); for (int r = 0; r < 16; ++r) pmax = fmaxf(pmax, p1[r]);
;   { auto rr = __builtin_amdgcn_permlane32_swap(__float_as_uint(pmax), __float_as_uint(pmax), false, false);
;     pmax = fmaxf(__uint_as_float(rr[0]), __uint_as_float(rr[1])); }
;   if (__builtin_expect(__all(pmax - m_reg <= THR / SCALE), 1)) { mn = m_reg; alpha = 1.f; }
;   else { mn = fmaxf(m_reg, pmax); alpha = __builtin_amdgcn_exp2f((m_reg - mn) * C); m_reg = mn; }
;   float mnC = -mn * C;
;   for (int r = 0; r < 16; ++r) p0[r] = fmaf(p0[r], C, mnC); for (int r = 0; r < 16; ++r) p1[r] = fmaf(p1[r], C, mnC);
;   for (int r = 0; r < 16; ++r) p0[r] = __builtin_amdgcn_exp2f(p0[r]);
; }
; __device__ __forceinline__ void finishSM(f32x16& p0, f32x16& p1, float alpha, float& l_reg, bf16x8& pa0, bf16x8& pa1, bf16x8& pa2, bf16x8& pa3) {
;   for (int r = 0; r < 16; ++r) p1[r] = __builtin_amdgcn_exp2f(p1[r]);
;   float ps = 0; for (int r = 0; r < 16; ++r) ps += p0[r]; for (int r = 0; r < 16; ++r) ps += p1[r];
;   { auto rr = __builtin_amdgcn_permlane32_swap(__float_as_uint(ps), __float_as_uint(ps), false, false);
;     ps = __uint_as_float(rr[0]) + __uint_as_float(rr[1]); }
;   l_reg = l_reg * alpha + ps;
;     ...
;   PK4(p0, 0, pa0); PK4(p0, 8, pa1); PK4(p1, 0, pa2); PK4(p1, 8, pa3);
;     ...
; }
; __device__ __forceinline__ void attn_unit(const bf16* __restrict__ Qb, const bf16* __restrict__ Kh, const bf16* __restrict__ Vh, int klat0, int nlt, int kctx0, int NT,
;                                           float lam, float post, const float* __restrict__ subw, bf16* __restrict__ Ob, char* lds) {
;     ...
;     for (int j = 1; j + 1 < NT; j += 2) {
;       if (j + 2 < NT) DMA_TILE(j + 2);
;       SBAR(); qkt(pB0, pB1, KS(j), qr, r32, hi, sb);
;       finishSM(pA0, pA1, alA, l_reg, pa0, pa1, pa2, pa3); SBAR();
;       pv_d0(o, VB(j - 1), pa0, pa1, pa2, pa3); partialSM(pB0, pB1, m_reg, mnB, alB);
	v_cmp_gt_u32_e64 s[40:41], 32, v66
	v_lshl_add_u32 v135, v124, 2, s11
	v_mfma_f32_32x32x16_bf16 v[18:33], v[40:43], v[116:119], v[18:33]
	v_mfma_f32_32x32x16_bf16 v[2:17], v[6:9], v[120:123], 0
	v_mfma_f32_32x32x16_bf16 v[18:33], v[48:51], v[112:115], v[18:33]
	v_mfma_f32_32x32x16_bf16 v[2:17], v[44:47], v[116:119], v[2:17]
	v_mfma_f32_32x32x16_bf16 v[18:33], v[56:59], v[108:111], v[18:33]
	v_mfma_f32_32x32x16_bf16 v[2:17], v[52:55], v[112:115], v[2:17]
	s_nop 10
	v_max_f32_e32 v40, v19, v19
	v_max_f32_e32 v41, v18, v18
	v_max_f32_e32 v40, v41, v40
	v_max3_f32 v40, v40, v20, v21
	v_max3_f32 v40, v40, v22, v23
	v_max3_f32 v40, v40, v24, v25
	v_max3_f32 v40, v40, v26, v27
	v_mfma_f32_32x32x16_bf16 v[2:17], v[60:63], v[108:111], v[2:17]
	v_max3_f32 v40, v40, v28, v29
	v_max3_f32 v40, v40, v30, v31
	v_max3_f32 v40, v40, v32, v33
	s_nop 8
	v_max3_f32 v40, v40, v2, v3
	v_max3_f32 v40, v40, v4, v5
	v_max3_f32 v40, v40, v6, v7
	v_max3_f32 v40, v40, v8, v9
	v_max3_f32 v40, v40, v10, v11
	v_max3_f32 v40, v40, v12, v13
	v_max3_f32 v40, v40, v14, v15
	v_max3_f32 v40, v40, v16, v17
	v_mov_b32_e32 v41, v40
	s_nop 1
	v_permlane32_swap_b32_e32 v40, v41
	v_max_f32_e32 v41, v41, v41
	v_max_f32_e32 v40, v40, v40
	v_max_f32_e32 v40, v40, v41
	v_add_f32_e32 v41, 0x7149f2ca, v40
	v_cmp_ge_f32_e32 vcc, s63, v41
	s_cmp_eq_u64 vcc, exec
	v_max_f32_e32 v40, 0xf149f2ca, v40
	s_cselect_b64 vcc, -1, 0
	v_cndmask_b32_e32 v142, v40, v248, vcc
	v_sub_f32_e32 v41, 0xf149f2ca, v40
	v_mul_f32_e32 v40, 0xbe38aa3b, v142
	v_fmamk_f32 v18, v18, 0x3e38aa3b, v40
	s_cmpk_lt_u32 s16, 0x100
	v_mul_f32_e32 v41, 0x3e38aa3b, v41
	v_fmamk_f32 v19, v19, 0x3e38aa3b, v40
	v_exp_f32_e32 v203, v18
	s_cselect_b64 s[4:5], -1, 0
	s_or_b32 s0, s0, 0x60000
	v_exp_f32_e32 v41, v41
	v_fmamk_f32 v20, v20, 0x3e38aa3b, v40
	v_fmamk_f32 v21, v21, 0x3e38aa3b, v40
	v_fmamk_f32 v22, v22, 0x3e38aa3b, v40
	v_fmamk_f32 v23, v23, 0x3e38aa3b, v40
	v_fmamk_f32 v24, v24, 0x3e38aa3b, v40
	v_fmamk_f32 v25, v25, 0x3e38aa3b, v40
	v_fmamk_f32 v26, v26, 0x3e38aa3b, v40
	v_fmamk_f32 v27, v27, 0x3e38aa3b, v40
	v_fmamk_f32 v28, v28, 0x3e38aa3b, v40
	v_fmamk_f32 v29, v29, 0x3e38aa3b, v40
	v_fmamk_f32 v30, v30, 0x3e38aa3b, v40
	v_fmamk_f32 v31, v31, 0x3e38aa3b, v40
	v_fmamk_f32 v32, v32, 0x3e38aa3b, v40
	v_fmamk_f32 v33, v33, 0x3e38aa3b, v40
	v_fmamk_f32 v2, v2, 0x3e38aa3b, v40
	v_fmamk_f32 v3, v3, 0x3e38aa3b, v40
	v_fmamk_f32 v4, v4, 0x3e38aa3b, v40
	v_fmamk_f32 v5, v5, 0x3e38aa3b, v40
	v_fmamk_f32 v6, v6, 0x3e38aa3b, v40
	v_fmamk_f32 v7, v7, 0x3e38aa3b, v40
	v_fmamk_f32 v8, v8, 0x3e38aa3b, v40
	v_fmamk_f32 v9, v9, 0x3e38aa3b, v40
	v_fmamk_f32 v10, v10, 0x3e38aa3b, v40
	v_fmamk_f32 v11, v11, 0x3e38aa3b, v40
	v_fmamk_f32 v12, v12, 0x3e38aa3b, v40
	v_fmamk_f32 v13, v13, 0x3e38aa3b, v40
	v_fmamk_f32 v14, v14, 0x3e38aa3b, v40
	v_fmamk_f32 v15, v15, 0x3e38aa3b, v40
	v_fmamk_f32 v16, v16, 0x3e38aa3b, v40
	v_fmac_f32_e32 v40, 0x3e38aa3b, v17
	v_exp_f32_e32 v205, v19
	s_add_u32 s20, s17, s0
	v_exp_f32_e32 v201, v20
	v_exp_f32_e32 v204, v21
	v_exp_f32_e32 v198, v22
	v_exp_f32_e32 v202, v23
	v_exp_f32_e32 v195, v24
	v_exp_f32_e32 v199, v25
	v_exp_f32_e32 v165, v26
	v_exp_f32_e32 v167, v27
	v_exp_f32_e32 v163, v28
	v_exp_f32_e32 v166, v29
	v_exp_f32_e32 v155, v30
	v_exp_f32_e32 v164, v31
	v_exp_f32_e32 v154, v32
	v_exp_f32_e32 v162, v33
	s_addc_u32 s21, s18, s1
	v_exp_f32_e32 v176, v2
	v_exp_f32_e32 v177, v3
	v_exp_f32_e32 v192, v4
	v_exp_f32_e32 v193, v5
	v_exp_f32_e32 v194, v6
	v_exp_f32_e32 v196, v7
	v_exp_f32_e32 v197, v8
	v_exp_f32_e32 v200, v9
	v_exp_f32_e32 v168, v10
	v_exp_f32_e32 v169, v11
	v_exp_f32_e32 v170, v12
	v_exp_f32_e32 v171, v13
	v_exp_f32_e32 v172, v14
	v_exp_f32_e32 v173, v15
	v_exp_f32_e32 v174, v16
	v_exp_f32_e32 v175, v40
	s_add_u32 s0, s6, s0
	s_addc_u32 s1, s7, s1
	v_add_f32_e32 v2, 0, v203
	v_cndmask_b32_e64 v141, v41, 1.0, vcc
	s_cmpk_gt_u32 s16, 0xff
	v_lshl_add_u64 v[126:127], s[20:21], 0, v[64:65]
	v_lshl_add_u64 v[128:129], s[0:1], 0, v[38:39]
	v_lshl_add_u64 v[130:131], s[20:21], 0, v[36:37]
	v_lshl_add_u64 v[132:133], s[0:1], 0, v[34:35]
	s_mov_b64 s[0:1], -1
	v_max_f32_e32 v145, v142, v142
	v_add_f32_e32 v206, v205, v2
	s_cbranch_scc0 .LBB0_727
	s_cmp_lg_u32 0, -1
	s_cselect_b32 s0, 0, 0
	s_add_i32 s0, s0, s13
	s_add_i32 s6, s13, 0
	.p2align 8
	s_add_i32 s1, s0, 0x18000
	s_mov_b32 m0, s6
	s_nop 0
	global_load_lds_dwordx4 v[132:133], off
	s_mov_b32 m0, s1
	s_nop 0
	global_load_lds_dwordx4 v[130:131], off
	s_add_i32 m0, s6, 0x2000
	s_nop 0
	global_load_lds_dwordx4 v[128:129], off
	s_add_i32 m0, s0, 0x1a000
	s_nop 0
	global_load_lds_dwordx4 v[126:127], off
	ds_read_b128 v[2:5], v137 offset:16384
	ds_read_b128 v[6:9], v137 offset:24576
	ds_read_b128 v[10:13], v138 offset:16384
	ds_read_b128 v[14:17], v138 offset:24576
	ds_read_b128 v[18:21], v139 offset:16384
	ds_read_b128 v[22:25], v139 offset:24576
	ds_read_b128 v[26:29], v140 offset:16384
	ds_read_b128 v[30:33], v140 offset:24576
	v_add_f32_e32 v34, v201, v206
	v_add_f32_e32 v34, v204, v34
	v_add_f32_e32 v34, v198, v34
	v_add_f32_e32 v34, v202, v34
	v_add_f32_e32 v34, v195, v34
	v_add_f32_e32 v34, v199, v34
	v_add_f32_e32 v34, v165, v34
	v_add_f32_e32 v34, v167, v34
	v_add_f32_e32 v34, v163, v34
	v_add_f32_e32 v34, v166, v34
	v_add_f32_e32 v34, v155, v34
	v_add_f32_e32 v34, v164, v34
	v_add_f32_e32 v34, v154, v34
	v_add_f32_e32 v34, v162, v34
	v_add_f32_e32 v34, v176, v34
	v_add_f32_e32 v34, v177, v34
	v_add_f32_e32 v34, v192, v34
	v_add_f32_e32 v34, v193, v34
	v_add_f32_e32 v34, v194, v34
	v_add_f32_e32 v34, v196, v34
	v_add_f32_e32 v34, v197, v34
	v_add_f32_e32 v34, v200, v34
	v_add_f32_e32 v34, v168, v34
	v_add_f32_e32 v34, v169, v34
	v_add_f32_e32 v34, v170, v34
	v_add_f32_e32 v34, v171, v34
	v_add_f32_e32 v34, v172, v34
	v_add_f32_e32 v34, v173, v34
	v_add_f32_e32 v34, v174, v34
	v_add_f32_e32 v106, v175, v34
	v_mov_b32_e32 v107, v106
	v_cvt_pk_bf16_f32 v50, v203, v205
	v_cvt_pk_bf16_f32 v51, v201, v204
	v_cvt_pk_bf16_f32 v52, v198, v202
	v_cvt_pk_bf16_f32 v53, v195, v199
	s_nop 1
	v_permlane32_swap_b32_e32 v106, v107
	v_permlane32_swap_b32_e32 v50, v52
	v_permlane32_swap_b32_e32 v51, v53
	v_cvt_pk_bf16_f32 v98, v165, v167
	v_cvt_pk_bf16_f32 v99, v163, v166
	v_cvt_pk_bf16_f32 v100, v155, v164
	v_cvt_pk_bf16_f32 v101, v154, v162
	v_cvt_pk_bf16_f32 v148, v176, v177
	v_cvt_pk_bf16_f32 v149, v192, v193
	v_cvt_pk_bf16_f32 v150, v194, v196
	v_cvt_pk_bf16_f32 v151, v197, v200
	v_cvt_pk_bf16_f32 v186, v168, v169
	v_cvt_pk_bf16_f32 v187, v170, v171
	v_cvt_pk_bf16_f32 v188, v172, v173
	v_cvt_pk_bf16_f32 v189, v174, v175
	s_nop 0
	v_permlane32_swap_b32_e32 v98, v100
	v_permlane32_swap_b32_e32 v99, v101
	v_permlane32_swap_b32_e32 v148, v150
	v_permlane32_swap_b32_e32 v149, v151
	v_permlane32_swap_b32_e32 v186, v188
	v_permlane32_swap_b32_e32 v187, v189
	s_waitcnt lgkmcnt(0)
; __device__ __forceinline__ void partialSM(f32x16& p0, f32x16& p1, float& m_reg, float& mn, float& alpha) {
;   constexpr float C = SCALE * 1.4426950408889634f;
;   float pmax = p0[0]; for (int r = 1; r < 16; ++r) pmax = fmaxf(pmax, p0[r]); for (int r = 0; r < 16; ++r) pmax = fmaxf(pmax, p1[r]);
;   { auto rr = __builtin_amdgcn_permlane32_swap(__float_as_uint(pmax), __float_as_uint(pmax), false, false);
;     pmax = fmaxf(__uint_as_float(rr[0]), __uint_as_float(rr[1])); }
;   if (__builtin_expect(__all(pmax - m_reg <= THR / SCALE), 1)) { mn = m_reg; alpha = 1.f; }
;   else { mn = fmaxf(m_reg, pmax); alpha = __builtin_amdgcn_exp2f((m_reg - mn) * C); m_reg = mn; }
;   float mnC = -mn * C;
;   for (int r = 0; r < 16; ++r) p0[r] = fmaf(p0[r], C, mnC); for (int r = 0; r < 16; ++r) p1[r] = fmaf(p1[r], C, mnC);
;   for (int r = 0; r < 16; ++r) p0[r] = __builtin_amdgcn_exp2f(p0[r]);
; }
; __device__ __forceinline__ void finishSM(f32x16& p0, f32x16& p1, float alpha, float& l_reg, bf16x8& pa0, bf16x8& pa1, bf16x8& pa2, bf16x8& pa3) {
;   for (int r = 0; r < 16; ++r) p1[r] = __builtin_amdgcn_exp2f(p1[r]);
;   float ps = 0; for (int r = 0; r < 16; ++r) ps += p0[r]; for (int r = 0; r < 16; ++r) ps += p1[r];
;   { auto rr = __builtin_amdgcn_permlane32_swap(__float_as_uint(ps), __float_as_uint(ps), false, false);
;     ps = __uint_as_float(rr[0]) + __uint_as_float(rr[1]); }
;   l_reg = l_reg * alpha + ps;
;     ...
;   PK4(p0, 0, pa0); PK4(p0, 8, pa1); PK4(p1, 0, pa2); PK4(p1, 8, pa3);
;     ...
; }
; __device__ __forceinline__ void kload(bf16x8 (&kf)[8], const char* Ks, int r32, int hi, int sb) {
; #pragma unroll
;   for (int d0 = 0; d0 < 4; ++d0) { const int cb = sb + (d0 * 16 + hi * 8) * 2;
;     kf[2 * d0] = *reinterpret_cast<const bf16x8*>(Ks + KSWZ(r32, cb)); kf[2 * d0 + 1] = *reinterpret_cast<const bf16x8*>(Ks + KSWZ(32 + r32, cb)); }
; }
; __device__ __forceinline__ void kmma(f32x16& p0, f32x16& p1, const bf16x8 (&kf)[8], const bf16x8* qr) {
;   asm volatile("s_waitcnt lgkmcnt(0)" ::: "memory"); SBAR();
;   p0 = f32x16{}; p1 = f32x16{};
; #pragma unroll
;   for (int d0 = 0; d0 < 4; ++d0) { p0 = __builtin_amdgcn_mfma_f32_32x32x16_bf16(kf[2 * d0], qr[d0], p0, 0, 0, 0); p1 = __builtin_amdgcn_mfma_f32_32x32x16_bf16(kf[2 * d0 + 1], qr[d0], p1, 0, 0, 0); }
; }
; __device__ __forceinline__ void pv_mma(f32x16& od, const VFrag& f, bf16x8 pa0, bf16x8 pa1, bf16x8 pa2, bf16x8 pa3) {
	s_waitcnt lgkmcnt(0)
	v_mfma_f32_32x32x16_bf16 v[82:97], v[2:5], v[120:123], 0
	v_mfma_f32_32x32x16_bf16 v[66:81], v[6:9], v[120:123], 0
	v_mfma_f32_32x32x16_bf16 v[82:97], v[10:13], v[116:119], v[82:97]
	v_mfma_f32_32x32x16_bf16 v[66:81], v[14:17], v[116:119], v[66:81]
	v_mfma_f32_32x32x16_bf16 v[82:97], v[18:21], v[112:115], v[82:97]
	v_mfma_f32_32x32x16_bf16 v[66:81], v[22:25], v[112:115], v[66:81]
	v_mfma_f32_32x32x16_bf16 v[82:97], v[26:29], v[108:111], v[82:97]
	v_mfma_f32_32x32x16_bf16 v[66:81], v[30:33], v[108:111], v[66:81]
	s_nop 10
	v_max_f32_e32 v2, v83, v83
	v_max_f32_e32 v3, v82, v82
	v_max_f32_e32 v2, v3, v2
	v_max3_f32 v2, v2, v84, v85
	v_max3_f32 v2, v2, v86, v87
	v_max3_f32 v2, v2, v88, v89
	v_max3_f32 v2, v2, v90, v91
	v_max3_f32 v2, v2, v92, v93
	v_max3_f32 v2, v2, v94, v95
	v_max3_f32 v2, v2, v96, v97
	v_max3_f32 v2, v2, v66, v67
	v_max3_f32 v2, v2, v68, v69
	v_max3_f32 v2, v2, v70, v71
	v_max3_f32 v2, v2, v72, v73
	v_max3_f32 v2, v2, v74, v75
	v_max3_f32 v2, v2, v76, v77
	v_max3_f32 v2, v2, v78, v79
	v_max3_f32 v2, v2, v80, v81
	v_mov_b32_e32 v3, v2
	s_nop 1
	v_permlane32_swap_b32_e32 v2, v3
	v_max_f32_e32 v3, v3, v3
	v_max_f32_e32 v2, v2, v2
	v_max_f32_e32 v2, v2, v3
	v_max_f32_e32 v102, v145, v2
	v_sub_f32_e32 v3, v2, v142
	v_sub_f32_e32 v2, v142, v102
	v_mul_f32_e32 v2, 0x3e38aa3b, v2
	v_exp_f32_e32 v2, v2
	v_cmp_ge_f32_e32 vcc, s63, v3
	s_cmp_eq_u64 vcc, exec
	s_cselect_b64 s[0:1], -1, 0
	v_cndmask_b32_e64 v208, v2, 1.0, s[0:1]
	ds_read_b64_tr_b16 v[2:3], v144 offset:0
	ds_read_b64_tr_b16 v[4:5], v144 offset:0x800
	ds_read_b64_tr_b16 v[18:19], v144 offset:0x1000
	ds_read_b64_tr_b16 v[20:21], v144 offset:0x1800
	ds_read_b64_tr_b16 v[22:23], v144 offset:0x2000
	ds_read_b64_tr_b16 v[24:25], v144 offset:0x2800
	ds_read_b64_tr_b16 v[26:27], v144 offset:0x3000
	ds_read_b64_tr_b16 v[28:29], v144 offset:0x3800
	s_waitcnt lgkmcnt(0)
	ds_read_b64_tr_b16 v[30:31], v144 offset:0x200
	ds_read_b64_tr_b16 v[32:33], v144 offset:0xa00
	ds_read_b64_tr_b16 v[34:35], v144 offset:0x1200
	ds_read_b64_tr_b16 v[36:37], v144 offset:0x1a00
	ds_read_b64_tr_b16 v[38:39], v144 offset:0x2200
	ds_read_b64_tr_b16 v[40:41], v144 offset:0x2a00
	ds_read_b64_tr_b16 v[42:43], v144 offset:0x3200
	ds_read_b64_tr_b16 v[44:45], v144 offset:0x3a00
	s_nop 0
	v_mfma_f32_32x32x16_bf16 v[2:17], v[50:53], v[2:5], 0
	v_mfma_f32_32x32x16_bf16 v[2:17], v[98:101], v[18:21], v[2:17]
	v_mfma_f32_32x32x16_bf16 v[2:17], v[148:151], v[22:25], v[2:17]
	v_mfma_f32_32x32x16_bf16 v[2:17], v[186:189], v[26:29], v[2:17]
	s_waitcnt lgkmcnt(0)
	ds_read_b64_tr_b16 v[46:47], v144 offset:0x400
	ds_read_b64_tr_b16 v[48:49], v144 offset:0xc00
	ds_read_b64_tr_b16 v[54:55], v144 offset:0x1400
	ds_read_b64_tr_b16 v[56:57], v144 offset:0x1c00
	ds_read_b64_tr_b16 v[58:59], v144 offset:0x2400
	ds_read_b64_tr_b16 v[60:61], v144 offset:0x2c00
	ds_read_b64_tr_b16 v[62:63], v144 offset:0x3400
	ds_read_b64_tr_b16 v[64:65], v144 offset:0x3c00
	v_mfma_f32_32x32x16_bf16 v[18:33], v[50:53], v[30:33], 0
	v_mfma_f32_32x32x16_bf16 v[18:33], v[98:101], v[34:37], v[18:33]
	v_mfma_f32_32x32x16_bf16 v[18:33], v[148:151], v[38:41], v[18:33]
	v_mfma_f32_32x32x16_bf16 v[18:33], v[186:189], v[42:45], v[18:33]
	s_waitcnt lgkmcnt(0)
	ds_read_b64_tr_b16 v[210:211], v144 offset:0x600
	ds_read_b64_tr_b16 v[212:213], v144 offset:0xe00
	ds_read_b64_tr_b16 v[214:215], v144 offset:0x1600
	ds_read_b64_tr_b16 v[216:217], v144 offset:0x1e00
	ds_read_b64_tr_b16 v[218:219], v144 offset:0x2600
	ds_read_b64_tr_b16 v[220:221], v144 offset:0x2e00
	ds_read_b64_tr_b16 v[222:223], v144 offset:0x3600
	ds_read_b64_tr_b16 v[224:225], v144 offset:0x3e00
	v_mfma_f32_32x32x16_bf16 v[34:49], v[50:53], v[46:49], 0
	v_mfma_f32_32x32x16_bf16 v[34:49], v[98:101], v[54:57], v[34:49]
	v_mfma_f32_32x32x16_bf16 v[34:49], v[148:151], v[58:61], v[34:49]
	v_mfma_f32_32x32x16_bf16 v[34:49], v[186:189], v[62:65], v[34:49]
	s_waitcnt lgkmcnt(0)
	v_mfma_f32_32x32x16_bf16 v[50:65], v[50:53], v[210:213], 0
	v_cmp_gt_f32_e32 vcc, 1.0, v208
	v_mfma_f32_32x32x16_bf16 v[50:65], v[98:101], v[214:217], v[50:65]
	v_mfma_f32_32x32x16_bf16 v[50:65], v[148:151], v[218:221], v[50:65]
	v_mfma_f32_32x32x16_bf16 v[50:65], v[186:189], v[222:225], v[50:65]
	s_cbranch_vccz .LBB0_722
	s_and_saveexec_b64 s[6:7], s[40:41]
	ds_write_b32 v135, v208 offset:128
	s_or_b64 exec, exec, s[6:7]
	s_waitcnt lgkmcnt(0)
	v_add_u32_e32 v103, s11, v146
	ds_read_b128 v[98:101], v103 offset:224
	ds_read_b128 v[148:151], v103 offset:192
	ds_read_b128 v[186:189], v103 offset:160
	ds_read_b128 v[210:213], v103 offset:128
	s_waitcnt lgkmcnt(0)
	v_pk_mul_f32 v[14:15], v[14:15], v[98:99]
	v_pk_mul_f32 v[10:11], v[10:11], v[148:149]
	v_pk_mul_f32 v[6:7], v[6:7], v[186:187]
	v_pk_mul_f32 v[16:17], v[16:17], v[100:101]
	v_pk_mul_f32 v[12:13], v[12:13], v[150:151]
	v_pk_mul_f32 v[8:9], v[8:9], v[188:189]
	v_pk_mul_f32 v[4:5], v[4:5], v[212:213]
	v_pk_mul_f32 v[2:3], v[2:3], v[210:211]
	v_pk_mul_f32 v[30:31], v[30:31], v[98:99]
	v_pk_mul_f32 v[26:27], v[26:27], v[148:149]
	v_pk_mul_f32 v[22:23], v[22:23], v[186:187]
	v_pk_mul_f32 v[32:33], v[32:33], v[100:101]
	v_pk_mul_f32 v[28:29], v[28:29], v[150:151]
	v_pk_mul_f32 v[24:25], v[24:25], v[188:189]
	v_pk_mul_f32 v[20:21], v[20:21], v[212:213]
	v_pk_mul_f32 v[18:19], v[18:19], v[210:211]
	v_pk_mul_f32 v[46:47], v[46:47], v[98:99]
	v_pk_mul_f32 v[42:43], v[42:43], v[148:149]
	v_pk_mul_f32 v[38:39], v[38:39], v[186:187]
	v_pk_mul_f32 v[48:49], v[48:49], v[100:101]
	v_pk_mul_f32 v[44:45], v[44:45], v[150:151]
	v_pk_mul_f32 v[40:41], v[40:41], v[188:189]
	v_pk_mul_f32 v[36:37], v[36:37], v[212:213]
	v_pk_mul_f32 v[34:35], v[34:35], v[210:211]
	v_pk_mul_f32 v[62:63], v[62:63], v[98:99]
	v_pk_mul_f32 v[58:59], v[58:59], v[148:149]
	v_pk_mul_f32 v[54:55], v[54:55], v[186:187]
	v_pk_mul_f32 v[64:65], v[64:65], v[100:101]
	v_pk_mul_f32 v[60:61], v[60:61], v[150:151]
	v_pk_mul_f32 v[56:57], v[56:57], v[188:189]
	v_pk_mul_f32 v[52:53], v[52:53], v[212:213]
	v_pk_mul_f32 v[50:51], v[50:51], v[210:211]
